# v38 + write-through (sc1) residual stores in the out-proj epilogue
# speedup vs baseline: 1.0036x; 1.0036x over previous
; template <int MODE, bool SWAP, int MT>
; DI void gemm_tile(const int wv_, const Params& p, const u16* __restrict__ A, const u16* __restrict__ Bt, int brow, int bcol, char* smem, const float* gnext) {
;     ...
;         for (int n = 0; n < 4; ++n) {
;           int col = bcol + wc * 64 + n * 16 + fq * 4;
;           float4 v = make_float4(0.f, 0.f, 0.f, 0.f);
;           if (valid) {
;             v = *(float4*)(hr + col);
;             v.x += acc[m][n][0]; v.y += acc[m][n][1]; v.z += acc[m][n][2]; v.w += acc[m][n][3];
;             *(float4*)(hr + col) = v;
.LBB0_832:
	s_or_b64 exec, exec, s[0:1]
	v_lshrrev_b32_e32 v1, 2, v77
	v_lshlrev_b32_e32 v0, 6, v76
	v_and_b32_e32 v1, 12, v1
	v_or3_b32 v0, v0, v1, s12
	v_mov_b32_e32 v2, 0
	v_ashrrev_i32_e32 v1, 31, v0
	v_mov_b32_e32 v66, 0
	v_mov_b32_e32 v67, 0
	v_mov_b32_e32 v64, 0
	v_mov_b32_e32 v65, 0
	s_and_saveexec_b64 s[0:1], s[2:3]
	s_cbranch_execz .LBB0_834
	v_lshl_add_u64 v[78:79], v[0:1], 2, v[74:75]
	global_load_dwordx4 v[64:67], v[78:79], off
	s_waitcnt vmcnt(0)
	v_pk_add_f32 v[64:65], v[68:69], v[64:65]
	v_pk_add_f32 v[66:67], v[70:71], v[66:67]
	global_store_dwordx4 v[78:79], v[64:67], off sc1

; template <int MODE, bool SWAP, int MT>
; DI void gemm_tile(const int wv_, const Params& p, const u16* __restrict__ A, const u16* __restrict__ Bt, int brow, int bcol, char* smem, const float* gnext) {
;     ...
;         for (int n = 0; n < 4; ++n) {
;           int col = bcol + wc * 64 + n * 16 + fq * 4;
;           float4 v = make_float4(0.f, 0.f, 0.f, 0.f);
;           if (valid) {
;             v = *(float4*)(hr + col);
;             v.x += acc[m][n][0]; v.y += acc[m][n][1]; v.z += acc[m][n][2]; v.w += acc[m][n][3];
;             *(float4*)(hr + col) = v;
.LBB0_836:
	v_mov_b32_e32 v66, 0
	v_mov_b32_e32 v67, 0
	v_mov_b32_e32 v64, 0
	v_mov_b32_e32 v65, 0
	s_and_saveexec_b64 s[4:5], s[2:3]
	s_cbranch_execz .LBB0_838
	v_lshl_add_u64 v[68:69], v[0:1], 2, v[74:75]
	global_load_dwordx4 v[64:67], v[68:69], off offset:64
	s_waitcnt vmcnt(0)
	v_pk_add_f32 v[64:65], v[60:61], v[64:65]
	v_pk_add_f32 v[66:67], v[62:63], v[66:67]
	global_store_dwordx4 v[68:69], v[64:67], off offset:64 sc1

; template <int MODE, bool SWAP, int MT>
; DI void gemm_tile(const int wv_, const Params& p, const u16* __restrict__ A, const u16* __restrict__ Bt, int brow, int bcol, char* smem, const float* gnext) {
;     ...
;         for (int n = 0; n < 4; ++n) {
;           int col = bcol + wc * 64 + n * 16 + fq * 4;
;           float4 v = make_float4(0.f, 0.f, 0.f, 0.f);
;           if (valid) {
;             v = *(float4*)(hr + col);
;             v.x += acc[m][n][0]; v.y += acc[m][n][1]; v.z += acc[m][n][2]; v.w += acc[m][n][3];
;             *(float4*)(hr + col) = v;
.LBB0_840:
	v_mov_b32_e32 v62, 0
	v_mov_b32_e32 v63, 0
	v_mov_b32_e32 v60, 0
	v_mov_b32_e32 v61, 0
	s_and_saveexec_b64 s[4:5], s[2:3]
	s_cbranch_execz .LBB0_842
	v_lshl_add_u64 v[64:65], v[0:1], 2, v[74:75]
	global_load_dwordx4 v[60:63], v[64:65], off offset:128
	s_waitcnt vmcnt(0)
	v_pk_add_f32 v[60:61], v[56:57], v[60:61]
	v_pk_add_f32 v[62:63], v[58:59], v[62:63]
	global_store_dwordx4 v[64:65], v[60:63], off offset:128 sc1

; template <int MODE, bool SWAP, int MT>
; DI void gemm_tile(const int wv_, const Params& p, const u16* __restrict__ A, const u16* __restrict__ Bt, int brow, int bcol, char* smem, const float* gnext) {
;     ...
;         for (int n = 0; n < 4; ++n) {
;           int col = bcol + wc * 64 + n * 16 + fq * 4;
;           float4 v = make_float4(0.f, 0.f, 0.f, 0.f);
;           if (valid) {
;             v = *(float4*)(hr + col);
;             v.x += acc[m][n][0]; v.y += acc[m][n][1]; v.z += acc[m][n][2]; v.w += acc[m][n][3];
;             *(float4*)(hr + col) = v;
.LBB0_844:
	v_mov_b32_e32 v58, 0
	v_mov_b32_e32 v59, 0
	v_mov_b32_e32 v56, 0
	v_mov_b32_e32 v57, 0
	s_and_saveexec_b64 s[4:5], s[2:3]
	s_cbranch_execz .LBB0_846
	v_lshl_add_u64 v[60:61], v[0:1], 2, v[74:75]
	global_load_dwordx4 v[56:59], v[60:61], off offset:192
	s_waitcnt vmcnt(0)
	v_pk_add_f32 v[56:57], v[52:53], v[56:57]
	v_pk_add_f32 v[58:59], v[54:55], v[58:59]
	global_store_dwordx4 v[60:61], v[56:59], off offset:192 sc1

; template <int MODE, bool SWAP, int MT>
; DI void gemm_tile(const int wv_, const Params& p, const u16* __restrict__ A, const u16* __restrict__ Bt, int brow, int bcol, char* smem, const float* gnext) {
;     ...
;         for (int n = 0; n < 4; ++n) {
;           int col = bcol + wc * 64 + n * 16 + fq * 4;
;           float4 v = make_float4(0.f, 0.f, 0.f, 0.f);
;           if (valid) {
;             v = *(float4*)(hr + col);
;             v.x += acc[m][n][0]; v.y += acc[m][n][1]; v.z += acc[m][n][2]; v.w += acc[m][n][3];
;             *(float4*)(hr + col) = v;
.LBB0_852:
	s_or_b64 exec, exec, s[14:15]
	v_mov_b32_e32 v2, 0
	v_mov_b32_e32 v54, 0
	v_mov_b32_e32 v55, 0
	v_mov_b32_e32 v52, 0
	s_waitcnt lgkmcnt(0)
	v_mov_b32_e32 v53, 0
	s_and_saveexec_b64 s[14:15], s[4:5]
	s_cbranch_execz .LBB0_854
	v_lshl_add_u64 v[58:59], v[0:1], 2, v[62:63]
	global_load_dwordx4 v[52:55], v[58:59], off
	s_waitcnt vmcnt(0)
	v_pk_add_f32 v[52:53], v[48:49], v[52:53]
	v_pk_add_f32 v[54:55], v[50:51], v[54:55]
	global_store_dwordx4 v[58:59], v[52:55], off sc1

; template <int MODE, bool SWAP, int MT>
; DI void gemm_tile(const int wv_, const Params& p, const u16* __restrict__ A, const u16* __restrict__ Bt, int brow, int bcol, char* smem, const float* gnext) {
;     ...
;         for (int n = 0; n < 4; ++n) {
;           int col = bcol + wc * 64 + n * 16 + fq * 4;
;           float4 v = make_float4(0.f, 0.f, 0.f, 0.f);
;           if (valid) {
;             v = *(float4*)(hr + col);
;             v.x += acc[m][n][0]; v.y += acc[m][n][1]; v.z += acc[m][n][2]; v.w += acc[m][n][3];
;             *(float4*)(hr + col) = v;
.LBB0_856:
	v_mov_b32_e32 v50, 0
	v_mov_b32_e32 v51, 0
	v_mov_b32_e32 v48, 0
	v_mov_b32_e32 v49, 0
	s_and_saveexec_b64 s[14:15], s[4:5]
	s_cbranch_execz .LBB0_858
	v_lshl_add_u64 v[52:53], v[0:1], 2, v[62:63]
	global_load_dwordx4 v[48:51], v[52:53], off offset:64
	s_waitcnt vmcnt(0)
	v_pk_add_f32 v[48:49], v[44:45], v[48:49]
	v_pk_add_f32 v[50:51], v[46:47], v[50:51]
	global_store_dwordx4 v[52:53], v[48:51], off offset:64 sc1

; template <int MODE, bool SWAP, int MT>
; DI void gemm_tile(const int wv_, const Params& p, const u16* __restrict__ A, const u16* __restrict__ Bt, int brow, int bcol, char* smem, const float* gnext) {
;     ...
;         for (int n = 0; n < 4; ++n) {
;           int col = bcol + wc * 64 + n * 16 + fq * 4;
;           float4 v = make_float4(0.f, 0.f, 0.f, 0.f);
;           if (valid) {
;             v = *(float4*)(hr + col);
;             v.x += acc[m][n][0]; v.y += acc[m][n][1]; v.z += acc[m][n][2]; v.w += acc[m][n][3];
;             *(float4*)(hr + col) = v;
.LBB0_860:
	v_mov_b32_e32 v46, 0
	v_mov_b32_e32 v47, 0
	v_mov_b32_e32 v44, 0
	v_mov_b32_e32 v45, 0
	s_and_saveexec_b64 s[14:15], s[4:5]
	s_cbranch_execz .LBB0_862
	v_lshl_add_u64 v[48:49], v[0:1], 2, v[62:63]
	global_load_dwordx4 v[44:47], v[48:49], off offset:128
	s_waitcnt vmcnt(0)
	v_pk_add_f32 v[44:45], v[40:41], v[44:45]
	v_pk_add_f32 v[46:47], v[42:43], v[46:47]
	global_store_dwordx4 v[48:49], v[44:47], off offset:128 sc1

; template <int MODE, bool SWAP, int MT>
; DI void gemm_tile(const int wv_, const Params& p, const u16* __restrict__ A, const u16* __restrict__ Bt, int brow, int bcol, char* smem, const float* gnext) {
;     ...
;         for (int n = 0; n < 4; ++n) {
;           int col = bcol + wc * 64 + n * 16 + fq * 4;
;           float4 v = make_float4(0.f, 0.f, 0.f, 0.f);
;           if (valid) {
;             v = *(float4*)(hr + col);
;             v.x += acc[m][n][0]; v.y += acc[m][n][1]; v.z += acc[m][n][2]; v.w += acc[m][n][3];
;             *(float4*)(hr + col) = v;
.LBB0_864:
	v_mov_b32_e32 v42, 0
	v_mov_b32_e32 v43, 0
	v_mov_b32_e32 v40, 0
	v_mov_b32_e32 v41, 0
	s_and_saveexec_b64 s[14:15], s[4:5]
	s_cbranch_execz .LBB0_866
	v_lshl_add_u64 v[44:45], v[0:1], 2, v[62:63]
	global_load_dwordx4 v[40:43], v[44:45], off offset:192
	s_waitcnt vmcnt(0)
	v_pk_add_f32 v[40:41], v[36:37], v[40:41]
	v_pk_add_f32 v[42:43], v[38:39], v[42:43]
	global_store_dwordx4 v[44:45], v[40:43], off offset:192 sc1

; template <int MODE, bool SWAP, int MT>
; DI void gemm_tile(const int wv_, const Params& p, const u16* __restrict__ A, const u16* __restrict__ Bt, int brow, int bcol, char* smem, const float* gnext) {
;     ...
;         for (int n = 0; n < 4; ++n) {
;           int col = bcol + wc * 64 + n * 16 + fq * 4;
;           float4 v = make_float4(0.f, 0.f, 0.f, 0.f);
;           if (valid) {
;             v = *(float4*)(hr + col);
;             v.x += acc[m][n][0]; v.y += acc[m][n][1]; v.z += acc[m][n][2]; v.w += acc[m][n][3];
;             *(float4*)(hr + col) = v;
.LBB0_872:
	s_or_b64 exec, exec, s[14:15]
	v_mov_b32_e32 v2, 0
	v_mov_b32_e32 v38, 0
	v_mov_b32_e32 v39, 0
	v_mov_b32_e32 v36, 0
	s_waitcnt lgkmcnt(0)
	v_mov_b32_e32 v37, 0
	s_and_saveexec_b64 s[14:15], s[4:5]
	s_cbranch_execz .LBB0_874
	v_lshl_add_u64 v[42:43], v[0:1], 2, v[44:45]
	global_load_dwordx4 v[36:39], v[42:43], off
	s_waitcnt vmcnt(0)
	v_pk_add_f32 v[36:37], v[32:33], v[36:37]
	v_pk_add_f32 v[38:39], v[34:35], v[38:39]
	global_store_dwordx4 v[42:43], v[36:39], off sc1

; template <int MODE, bool SWAP, int MT>
; DI void gemm_tile(const int wv_, const Params& p, const u16* __restrict__ A, const u16* __restrict__ Bt, int brow, int bcol, char* smem, const float* gnext) {
;     ...
;         for (int n = 0; n < 4; ++n) {
;           int col = bcol + wc * 64 + n * 16 + fq * 4;
;           float4 v = make_float4(0.f, 0.f, 0.f, 0.f);
;           if (valid) {
;             v = *(float4*)(hr + col);
;             v.x += acc[m][n][0]; v.y += acc[m][n][1]; v.z += acc[m][n][2]; v.w += acc[m][n][3];
;             *(float4*)(hr + col) = v;
.LBB0_876:
	v_mov_b32_e32 v34, 0
	v_mov_b32_e32 v35, 0
	v_mov_b32_e32 v32, 0
	v_mov_b32_e32 v33, 0
	s_and_saveexec_b64 s[14:15], s[4:5]
	s_cbranch_execz .LBB0_878
	v_lshl_add_u64 v[36:37], v[0:1], 2, v[44:45]
	global_load_dwordx4 v[32:35], v[36:37], off offset:64
	s_waitcnt vmcnt(0)
	v_pk_add_f32 v[32:33], v[28:29], v[32:33]
	v_pk_add_f32 v[34:35], v[30:31], v[34:35]
	global_store_dwordx4 v[36:37], v[32:35], off offset:64 sc1

; template <int MODE, bool SWAP, int MT>
; DI void gemm_tile(const int wv_, const Params& p, const u16* __restrict__ A, const u16* __restrict__ Bt, int brow, int bcol, char* smem, const float* gnext) {
;     ...
;         for (int n = 0; n < 4; ++n) {
;           int col = bcol + wc * 64 + n * 16 + fq * 4;
;           float4 v = make_float4(0.f, 0.f, 0.f, 0.f);
;           if (valid) {
;             v = *(float4*)(hr + col);
;             v.x += acc[m][n][0]; v.y += acc[m][n][1]; v.z += acc[m][n][2]; v.w += acc[m][n][3];
;             *(float4*)(hr + col) = v;
.LBB0_880:
	v_mov_b32_e32 v30, 0
	v_mov_b32_e32 v31, 0
	v_mov_b32_e32 v28, 0
	v_mov_b32_e32 v29, 0
	s_and_saveexec_b64 s[14:15], s[4:5]
	s_cbranch_execz .LBB0_882
	v_lshl_add_u64 v[32:33], v[0:1], 2, v[44:45]
	global_load_dwordx4 v[28:31], v[32:33], off offset:128
	s_waitcnt vmcnt(0)
	v_pk_add_f32 v[28:29], v[24:25], v[28:29]
	v_pk_add_f32 v[30:31], v[26:27], v[30:31]
	global_store_dwordx4 v[32:33], v[28:31], off offset:128 sc1

; template <int MODE, bool SWAP, int MT>
; DI void gemm_tile(const int wv_, const Params& p, const u16* __restrict__ A, const u16* __restrict__ Bt, int brow, int bcol, char* smem, const float* gnext) {
;     ...
;         for (int n = 0; n < 4; ++n) {
;           int col = bcol + wc * 64 + n * 16 + fq * 4;
;           float4 v = make_float4(0.f, 0.f, 0.f, 0.f);
;           if (valid) {
;             v = *(float4*)(hr + col);
;             v.x += acc[m][n][0]; v.y += acc[m][n][1]; v.z += acc[m][n][2]; v.w += acc[m][n][3];
;             *(float4*)(hr + col) = v;
.LBB0_884:
	v_mov_b32_e32 v26, 0
	v_mov_b32_e32 v27, 0
	v_mov_b32_e32 v24, 0
	v_mov_b32_e32 v25, 0
	s_and_saveexec_b64 s[14:15], s[4:5]
	s_cbranch_execz .LBB0_886
	v_lshl_add_u64 v[28:29], v[0:1], 2, v[44:45]
	global_load_dwordx4 v[24:27], v[28:29], off offset:192
	s_waitcnt vmcnt(0)
	v_pk_add_f32 v[24:25], v[20:21], v[24:25]
	v_pk_add_f32 v[26:27], v[22:23], v[26:27]
	global_store_dwordx4 v[28:29], v[24:27], off offset:192 sc1

; template <int MODE, bool SWAP, int MT>
; DI void gemm_tile(const int wv_, const Params& p, const u16* __restrict__ A, const u16* __restrict__ Bt, int brow, int bcol, char* smem, const float* gnext) {
;     ...
;         for (int n = 0; n < 4; ++n) {
;           int col = bcol + wc * 64 + n * 16 + fq * 4;
;           float4 v = make_float4(0.f, 0.f, 0.f, 0.f);
;           if (valid) {
;             v = *(float4*)(hr + col);
;             v.x += acc[m][n][0]; v.y += acc[m][n][1]; v.z += acc[m][n][2]; v.w += acc[m][n][3];
;             *(float4*)(hr + col) = v;
.LBB0_892:
	s_or_b64 exec, exec, s[14:15]
	v_mov_b32_e32 v2, 0
	v_mov_b32_e32 v22, 0
	v_mov_b32_e32 v23, 0
	v_mov_b32_e32 v20, 0
	s_waitcnt lgkmcnt(0)
	v_mov_b32_e32 v21, 0
	s_and_saveexec_b64 s[14:15], s[4:5]
	s_cbranch_execz .LBB0_894
	v_lshl_add_u64 v[26:27], v[0:1], 2, v[28:29]
	global_load_dwordx4 v[20:23], v[26:27], off
	s_waitcnt vmcnt(0)
	v_pk_add_f32 v[20:21], v[16:17], v[20:21]
	v_pk_add_f32 v[22:23], v[18:19], v[22:23]
	global_store_dwordx4 v[26:27], v[20:23], off sc1

; template <int MODE, bool SWAP, int MT>
; DI void gemm_tile(const int wv_, const Params& p, const u16* __restrict__ A, const u16* __restrict__ Bt, int brow, int bcol, char* smem, const float* gnext) {
;     ...
;         for (int n = 0; n < 4; ++n) {
;           int col = bcol + wc * 64 + n * 16 + fq * 4;
;           float4 v = make_float4(0.f, 0.f, 0.f, 0.f);
;           if (valid) {
;             v = *(float4*)(hr + col);
;             v.x += acc[m][n][0]; v.y += acc[m][n][1]; v.z += acc[m][n][2]; v.w += acc[m][n][3];
;             *(float4*)(hr + col) = v;
.LBB0_896:
	v_mov_b32_e32 v18, 0
	v_mov_b32_e32 v19, 0
	v_mov_b32_e32 v16, 0
	v_mov_b32_e32 v17, 0
	s_and_saveexec_b64 s[14:15], s[4:5]
	s_cbranch_execz .LBB0_898
	v_lshl_add_u64 v[20:21], v[0:1], 2, v[28:29]
	global_load_dwordx4 v[16:19], v[20:21], off offset:64
	s_waitcnt vmcnt(0)
	v_pk_add_f32 v[16:17], v[12:13], v[16:17]
	v_pk_add_f32 v[18:19], v[14:15], v[18:19]
	global_store_dwordx4 v[20:21], v[16:19], off offset:64 sc1

; template <int MODE, bool SWAP, int MT>
; DI void gemm_tile(const int wv_, const Params& p, const u16* __restrict__ A, const u16* __restrict__ Bt, int brow, int bcol, char* smem, const float* gnext) {
;     ...
;         for (int n = 0; n < 4; ++n) {
;           int col = bcol + wc * 64 + n * 16 + fq * 4;
;           float4 v = make_float4(0.f, 0.f, 0.f, 0.f);
;           if (valid) {
;             v = *(float4*)(hr + col);
;             v.x += acc[m][n][0]; v.y += acc[m][n][1]; v.z += acc[m][n][2]; v.w += acc[m][n][3];
;             *(float4*)(hr + col) = v;
.LBB0_900:
	v_mov_b32_e32 v14, 0
	v_mov_b32_e32 v15, 0
	v_mov_b32_e32 v12, 0
	v_mov_b32_e32 v13, 0
	s_and_saveexec_b64 s[14:15], s[4:5]
	s_cbranch_execz .LBB0_902
	v_lshl_add_u64 v[16:17], v[0:1], 2, v[28:29]
	global_load_dwordx4 v[12:15], v[16:17], off offset:128
	s_waitcnt vmcnt(0)
	v_pk_add_f32 v[12:13], v[8:9], v[12:13]
	v_pk_add_f32 v[14:15], v[10:11], v[14:15]
	global_store_dwordx4 v[16:17], v[12:15], off offset:128 sc1

; template <int MODE, bool SWAP, int MT>
; DI void gemm_tile(const int wv_, const Params& p, const u16* __restrict__ A, const u16* __restrict__ Bt, int brow, int bcol, char* smem, const float* gnext) {
;     ...
;         for (int n = 0; n < 4; ++n) {
;           int col = bcol + wc * 64 + n * 16 + fq * 4;
;           float4 v = make_float4(0.f, 0.f, 0.f, 0.f);
;           if (valid) {
;             v = *(float4*)(hr + col);
;             v.x += acc[m][n][0]; v.y += acc[m][n][1]; v.z += acc[m][n][2]; v.w += acc[m][n][3];
;             *(float4*)(hr + col) = v;
.LBB0_906:
	v_lshl_add_u64 v[12:13], v[0:1], 2, v[28:29]
	global_load_dwordx4 v[8:11], v[12:13], off offset:192
	s_waitcnt vmcnt(0)
	v_pk_add_f32 v[8:9], v[4:5], v[8:9]
	v_pk_add_f32 v[10:11], v[6:7], v[10:11]
	global_store_dwordx4 v[12:13], v[8:11], off offset:192 sc1
	s_or_b64 exec, exec, s[14:15]
	s_and_b64 vcc, exec, s[0:1]
	s_cbranch_vccnz .LBB0_827

; template <int MODE, bool SWAP, int MT>
; DI void gemm_tile(const int wv_, const Params& p, const u16* __restrict__ A, const u16* __restrict__ Bt, int brow, int bcol, char* smem, const float* gnext) {
;     ...
;   for (int t = 0; t < 32; ++t) {
;     asm volatile("s_waitcnt vmcnt(0)" ::: "memory");
;     __syncthreads();
;     if (t + 1 < 32) stage(t + 1, (t + 1) & 1);
;     const char* sA = smem + (t & 1) * 24576; const char* sB = sA + 16384;
;     bf16x8 Af[MT], Bf[4];
; #pragma unroll
;     for (int n = 0; n < 4; ++n) Bf[n] = *(const bf16x8*)(sB + (wc * 64 + n * 16 + fr) * 64 + fq * 16);
;     constexpr int MH = MT >= 2 ? MT / 2 : 1;
; #pragma unroll
;     for (int m = 0; m < MH; ++m) Af[m] = *(const bf16x8*)(sA + (wr * (16 * MT) + m * 16 + fr) * 64 + fq * 16);
;     __builtin_amdgcn_sched_barrier(0);
; #pragma unroll
;     for (int m = MH; m < MT; ++m) Af[m] = *(const bf16x8*)(sA + (wr * (16 * MT) + m * 16 + fr) * 64 + fq * 16);
; #pragma unroll
;     for (int m = 0; m < MH; ++m)
; #pragma unroll
;       for (int n = 0; n < 4; ++n)
;         acc[m][n] = SWAP ? __builtin_amdgcn_mfma_f32_16x16x32_bf16(Bf[n], Af[m], acc[m][n], 0, 0, 0)
;                          : __builtin_amdgcn_mfma_f32_16x16x32_bf16(Af[m], Bf[n], acc[m][n], 0, 0, 0);
;     __builtin_amdgcn_sched_barrier(0);
; #pragma unroll
;     for (int m = MH; m < MT; ++m)
; #pragma unroll
;       for (int n = 0; n < 4; ++n)
;         acc[m][n] = SWAP ? __builtin_amdgcn_mfma_f32_16x16x32_bf16(Bf[n], Af[m], acc[m][n], 0, 0, 0)
;                          : __builtin_amdgcn_mfma_f32_16x16x32_bf16(Af[m], Bf[n], acc[m][n], 0, 0, 0);
;   }
;   __syncthreads();
;   if (SWAP) {
; #pragma unroll
;     for (int m = 0; m < MT; ++m) {
;       int R = brow + wr * (16 * MT) + m * 16 + fr;
;       if (MODE == 2) {
;         int b = R / P, pos = R - b * P;
;         const bool valid = pos >= 112;
;         float* hr = valid ? hrow(p, b, pos) : nullptr;
;         float ssq = 0.f;
; #pragma unroll
;         for (int n = 0; n < 4; ++n) {
;           int col = bcol + wc * 64 + n * 16 + fq * 4;
;           float4 v = make_float4(0.f, 0.f, 0.f, 0.f);
;           if (valid) {
;             v = *(float4*)(hr + col);
;             v.x += acc[m][n][0]; v.y += acc[m][n][1]; v.z += acc[m][n][2]; v.w += acc[m][n][3];
;             *(float4*)(hr + col) = v;
.LBB0_978:
	s_or_b64 exec, exec, s[0:1]
	s_mov_b64 s[0:1], 0x7c0
	v_lshl_add_u64 v[0:1], v[20:21], 0, s[0:1]
	v_readfirstlane_b32 s0, v27
	s_mov_b32 m0, s0
	s_nop 0
	global_load_lds_dwordx4 v[0:1], off
	ds_read_b128 v[20:23], v26 offset:16384
	ds_read_b128 v[32:35], v26 offset:17408
	ds_read_b128 v[36:39], v26 offset:18432
	ds_read_b128 v[40:43], v26 offset:19456
	ds_read_b128 v[44:47], v30
	s_waitcnt lgkmcnt(0)
	v_mfma_f32_16x16x32_bf16 v[4:7], v[20:23], v[44:47], v[4:7]
	v_mfma_f32_16x16x32_bf16 v[8:11], v[32:35], v[44:47], v[8:11]
	v_mfma_f32_16x16x32_bf16 v[16:19], v[40:43], v[44:47], v[16:19]
	v_mfma_f32_16x16x32_bf16 v[32:35], v[36:39], v[44:47], v[12:15]
	s_waitcnt vmcnt(0)
	s_waitcnt vmcnt(0)
	s_barrier
	ds_read_b128 v[36:39], v30 offset:24576
	ds_read_b128 v[40:43], v26 offset:44032
	ds_read_b128 v[44:47], v26 offset:43008
	ds_read_b128 v[12:15], v26 offset:41984
	ds_read_b128 v[20:23], v26 offset:40960
	s_waitcnt lgkmcnt(0)
	v_mfma_f32_16x16x32_bf16 v[20:23], v[20:23], v[36:39], v[4:7]
	v_mfma_f32_16x16x32_bf16 v[12:15], v[12:15], v[36:39], v[8:11]
	v_mfma_f32_16x16x32_bf16 v[8:11], v[44:47], v[36:39], v[32:35]
	v_mfma_f32_16x16x32_bf16 v[4:7], v[40:43], v[36:39], v[16:19]
	v_or_b32_e32 v0, s2, v25
	v_lshl_add_u32 v0, v24, 4, v0
	s_mov_b32 s0, 0x7e07e07f
	v_mul_hi_i32 v1, v0, s0
	v_lshrrev_b32_e32 v16, 31, v1
	v_ashrrev_i32_e32 v1, 12, v1
	v_add_u32_e32 v1, v1, v16
	s_movk_i32 s0, 0xdf80
	v_mad_i32_i24 v16, v1, s0, v0
	s_movk_i32 s2, 0x7f
	v_cmp_lt_u32_e32 vcc, s2, v16
	v_mov_b32_e32 v18, 0xffffff90
	v_mov_b32_e32 v19, 0xffffff80
	v_cndmask_b32_e64 v17, 4, 13, vcc
	v_cndmask_b32_e32 v18, v18, v19, vcc
	v_lshlrev_b32_e32 v1, v17, v1
	v_cmp_lt_i32_e64 s[0:1], s54, v16
	v_add3_u32 v16, v18, v16, v1
	v_lshrrev_b32_e32 v18, 2, v28
	v_lshlrev_b32_e32 v1, 6, v2
	v_and_b32_e32 v18, 12, v18
	v_or3_b32 v24, v1, v18, s23
	v_mov_b32_e32 v1, s85
	v_mov_b32_e32 v18, s43
	v_ashrrev_i32_e32 v17, 31, v16
	v_cndmask_b32_e32 v19, v1, v18, vcc
	v_mov_b32_e32 v1, s84
	v_mov_b32_e32 v18, s42
	v_lshlrev_b64 v[16:17], 12, v[16:17]
	v_cndmask_b32_e32 v18, v1, v18, vcc
	v_lshl_add_u64 v[26:27], v[18:19], 0, v[16:17]
	v_mov_b32_e32 v29, 0
	v_ashrrev_i32_e32 v25, 31, v24
	v_mov_b32_e32 v18, 0
	v_mov_b32_e32 v19, 0
	v_mov_b32_e32 v16, 0
	v_mov_b32_e32 v17, 0
	s_barrier
	s_and_saveexec_b64 s[2:3], s[0:1]
	s_cbranch_execz .LBB0_980
	v_lshl_add_u64 v[30:31], v[24:25], 2, v[26:27]
	global_load_dwordx4 v[16:19], v[30:31], off
	s_waitcnt vmcnt(0)
	v_pk_add_f32 v[16:17], v[20:21], v[16:17]
	v_pk_add_f32 v[18:19], v[22:23], v[18:19]
	global_store_dwordx4 v[30:31], v[16:19], off sc1

; template <int MODE, bool SWAP, int MT>
; DI void gemm_tile(const int wv_, const Params& p, const u16* __restrict__ A, const u16* __restrict__ Bt, int brow, int bcol, char* smem, const float* gnext) {
;     ...
;         for (int n = 0; n < 4; ++n) {
;           int col = bcol + wc * 64 + n * 16 + fq * 4;
;           float4 v = make_float4(0.f, 0.f, 0.f, 0.f);
;           if (valid) {
;             v = *(float4*)(hr + col);
;             v.x += acc[m][n][0]; v.y += acc[m][n][1]; v.z += acc[m][n][2]; v.w += acc[m][n][3];
;             *(float4*)(hr + col) = v;
.LBB0_982:
	v_mov_b32_e32 v18, 0
	v_mov_b32_e32 v19, 0
	v_mov_b32_e32 v16, 0
	v_mov_b32_e32 v17, 0
	s_and_saveexec_b64 s[4:5], s[0:1]
	s_cbranch_execz .LBB0_984
	v_lshl_add_u64 v[22:23], v[24:25], 2, v[26:27]
	global_load_dwordx4 v[16:19], v[22:23], off offset:64
	s_waitcnt vmcnt(0)
	v_pk_add_f32 v[16:17], v[12:13], v[16:17]
	v_pk_add_f32 v[18:19], v[14:15], v[18:19]
	global_store_dwordx4 v[22:23], v[16:19], off offset:64 sc1

; template <int MODE, bool SWAP, int MT>
; DI void gemm_tile(const int wv_, const Params& p, const u16* __restrict__ A, const u16* __restrict__ Bt, int brow, int bcol, char* smem, const float* gnext) {
;     ...
;         for (int n = 0; n < 4; ++n) {
;           int col = bcol + wc * 64 + n * 16 + fq * 4;
;           float4 v = make_float4(0.f, 0.f, 0.f, 0.f);
;           if (valid) {
;             v = *(float4*)(hr + col);
;             v.x += acc[m][n][0]; v.y += acc[m][n][1]; v.z += acc[m][n][2]; v.w += acc[m][n][3];
;             *(float4*)(hr + col) = v;
.LBB0_986:
	v_mov_b32_e32 v14, 0
	v_mov_b32_e32 v15, 0
	v_mov_b32_e32 v12, 0
	v_mov_b32_e32 v13, 0
	s_and_saveexec_b64 s[4:5], s[0:1]
	s_cbranch_execz .LBB0_988
	v_lshl_add_u64 v[16:17], v[24:25], 2, v[26:27]
	global_load_dwordx4 v[12:15], v[16:17], off offset:128
	s_waitcnt vmcnt(0)
	v_pk_add_f32 v[12:13], v[8:9], v[12:13]
	v_pk_add_f32 v[14:15], v[10:11], v[14:15]
	global_store_dwordx4 v[16:17], v[12:15], off offset:128 sc1

; template <int MODE, bool SWAP, int MT>
; DI void gemm_tile(const int wv_, const Params& p, const u16* __restrict__ A, const u16* __restrict__ Bt, int brow, int bcol, char* smem, const float* gnext) {
;     ...
;         for (int n = 0; n < 4; ++n) {
;           int col = bcol + wc * 64 + n * 16 + fq * 4;
;           float4 v = make_float4(0.f, 0.f, 0.f, 0.f);
;           if (valid) {
;             v = *(float4*)(hr + col);
;             v.x += acc[m][n][0]; v.y += acc[m][n][1]; v.z += acc[m][n][2]; v.w += acc[m][n][3];
;             *(float4*)(hr + col) = v;
.LBB0_992:
	v_lshl_add_u64 v[12:13], v[24:25], 2, v[26:27]
	global_load_dwordx4 v[8:11], v[12:13], off offset:192
	s_waitcnt vmcnt(0)
	v_pk_add_f32 v[8:9], v[4:5], v[8:9]
	v_pk_add_f32 v[10:11], v[6:7], v[10:11]
	global_store_dwordx4 v[12:13], v[8:11], off offset:192 sc1
	s_or_b64 exec, exec, s[4:5]
	s_and_b64 vcc, exec, s[2:3]
	s_cbranch_vccnz .LBB0_913

; template <int MODE, bool SWAP, int MT>
; DI void gemm_tile(const int wv_, const Params& p, const u16* __restrict__ A, const u16* __restrict__ Bt, int brow, int bcol, char* smem, const float* gnext) {
;     ...
;         for (int n = 0; n < 4; ++n) {
;           int col = bcol + wc * 64 + n * 16 + fq * 4;
;           float4 v = make_float4(0.f, 0.f, 0.f, 0.f);
;           if (valid) {
;             v = *(float4*)(hr + col);
;             v.x += acc[m][n][0]; v.y += acc[m][n][1]; v.z += acc[m][n][2]; v.w += acc[m][n][3];
;             *(float4*)(hr + col) = v;
.LBB0_1005:
	s_or_b64 exec, exec, s[0:1]
	v_lshrrev_b32_e32 v1, 2, v45
	v_lshlrev_b32_e32 v0, 6, v44
	v_and_b32_e32 v1, 12, v1
	v_or3_b32 v0, v0, v1, s12
	v_mov_b32_e32 v2, 0
	v_ashrrev_i32_e32 v1, 31, v0
	v_mov_b32_e32 v34, 0
	v_mov_b32_e32 v35, 0
	v_mov_b32_e32 v32, 0
	v_mov_b32_e32 v33, 0
	s_and_saveexec_b64 s[0:1], s[2:3]
	s_cbranch_execz .LBB0_1007
	v_lshl_add_u64 v[46:47], v[0:1], 2, v[42:43]
	global_load_dwordx4 v[32:35], v[46:47], off
	s_waitcnt vmcnt(0)
	v_pk_add_f32 v[32:33], v[36:37], v[32:33]
	v_pk_add_f32 v[34:35], v[38:39], v[34:35]
	global_store_dwordx4 v[46:47], v[32:35], off sc1

; template <int MODE, bool SWAP, int MT>
; DI void gemm_tile(const int wv_, const Params& p, const u16* __restrict__ A, const u16* __restrict__ Bt, int brow, int bcol, char* smem, const float* gnext) {
;     ...
;         for (int n = 0; n < 4; ++n) {
;           int col = bcol + wc * 64 + n * 16 + fq * 4;
;           float4 v = make_float4(0.f, 0.f, 0.f, 0.f);
;           if (valid) {
;             v = *(float4*)(hr + col);
;             v.x += acc[m][n][0]; v.y += acc[m][n][1]; v.z += acc[m][n][2]; v.w += acc[m][n][3];
;             *(float4*)(hr + col) = v;
.LBB0_1009:
	v_mov_b32_e32 v34, 0
	v_mov_b32_e32 v35, 0
	v_mov_b32_e32 v32, 0
	v_mov_b32_e32 v33, 0
	s_and_saveexec_b64 s[4:5], s[2:3]
	s_cbranch_execz .LBB0_1011
	v_lshl_add_u64 v[36:37], v[0:1], 2, v[42:43]
	global_load_dwordx4 v[32:35], v[36:37], off offset:64
	s_waitcnt vmcnt(0)
	v_pk_add_f32 v[32:33], v[28:29], v[32:33]
	v_pk_add_f32 v[34:35], v[30:31], v[34:35]
	global_store_dwordx4 v[36:37], v[32:35], off offset:64 sc1

; template <int MODE, bool SWAP, int MT>
; DI void gemm_tile(const int wv_, const Params& p, const u16* __restrict__ A, const u16* __restrict__ Bt, int brow, int bcol, char* smem, const float* gnext) {
;     ...
;         for (int n = 0; n < 4; ++n) {
;           int col = bcol + wc * 64 + n * 16 + fq * 4;
;           float4 v = make_float4(0.f, 0.f, 0.f, 0.f);
;           if (valid) {
;             v = *(float4*)(hr + col);
;             v.x += acc[m][n][0]; v.y += acc[m][n][1]; v.z += acc[m][n][2]; v.w += acc[m][n][3];
;             *(float4*)(hr + col) = v;
.LBB0_1013:
	v_mov_b32_e32 v30, 0
	v_mov_b32_e32 v31, 0
	v_mov_b32_e32 v28, 0
	v_mov_b32_e32 v29, 0
	s_and_saveexec_b64 s[4:5], s[2:3]
	s_cbranch_execz .LBB0_1015
	v_lshl_add_u64 v[32:33], v[0:1], 2, v[42:43]
	global_load_dwordx4 v[28:31], v[32:33], off offset:128
	s_waitcnt vmcnt(0)
	v_pk_add_f32 v[28:29], v[24:25], v[28:29]
	v_pk_add_f32 v[30:31], v[26:27], v[30:31]
	global_store_dwordx4 v[32:33], v[28:31], off offset:128 sc1

; template <int MODE, bool SWAP, int MT>
; DI void gemm_tile(const int wv_, const Params& p, const u16* __restrict__ A, const u16* __restrict__ Bt, int brow, int bcol, char* smem, const float* gnext) {
;     ...
;         for (int n = 0; n < 4; ++n) {
;           int col = bcol + wc * 64 + n * 16 + fq * 4;
;           float4 v = make_float4(0.f, 0.f, 0.f, 0.f);
;           if (valid) {
;             v = *(float4*)(hr + col);
;             v.x += acc[m][n][0]; v.y += acc[m][n][1]; v.z += acc[m][n][2]; v.w += acc[m][n][3];
;             *(float4*)(hr + col) = v;
.LBB0_1017:
	v_mov_b32_e32 v26, 0
	v_mov_b32_e32 v27, 0
	v_mov_b32_e32 v24, 0
	v_mov_b32_e32 v25, 0
	s_and_saveexec_b64 s[4:5], s[2:3]
	s_cbranch_execz .LBB0_1019
	v_lshl_add_u64 v[28:29], v[0:1], 2, v[42:43]
	global_load_dwordx4 v[24:27], v[28:29], off offset:192
	s_waitcnt vmcnt(0)
	v_pk_add_f32 v[24:25], v[20:21], v[24:25]
	v_pk_add_f32 v[26:27], v[22:23], v[26:27]
	global_store_dwordx4 v[28:29], v[24:27], off offset:192 sc1

; template <int MODE, bool SWAP, int MT>
; DI void gemm_tile(const int wv_, const Params& p, const u16* __restrict__ A, const u16* __restrict__ Bt, int brow, int bcol, char* smem, const float* gnext) {
;     ...
;         for (int n = 0; n < 4; ++n) {
;           int col = bcol + wc * 64 + n * 16 + fq * 4;
;           float4 v = make_float4(0.f, 0.f, 0.f, 0.f);
;           if (valid) {
;             v = *(float4*)(hr + col);
;             v.x += acc[m][n][0]; v.y += acc[m][n][1]; v.z += acc[m][n][2]; v.w += acc[m][n][3];
;             *(float4*)(hr + col) = v;
.LBB0_1025:
	s_or_b64 exec, exec, s[14:15]
	v_mov_b32_e32 v2, 0
	v_mov_b32_e32 v22, 0
	v_mov_b32_e32 v23, 0
	v_mov_b32_e32 v20, 0
	s_waitcnt lgkmcnt(0)
	v_mov_b32_e32 v21, 0
	s_and_saveexec_b64 s[14:15], s[4:5]
	s_cbranch_execz .LBB0_1027
	v_lshl_add_u64 v[26:27], v[0:1], 2, v[30:31]
	global_load_dwordx4 v[20:23], v[26:27], off
	s_waitcnt vmcnt(0)
	v_pk_add_f32 v[20:21], v[16:17], v[20:21]
	v_pk_add_f32 v[22:23], v[18:19], v[22:23]
	global_store_dwordx4 v[26:27], v[20:23], off sc1

; template <int MODE, bool SWAP, int MT>
; DI void gemm_tile(const int wv_, const Params& p, const u16* __restrict__ A, const u16* __restrict__ Bt, int brow, int bcol, char* smem, const float* gnext) {
;     ...
;         for (int n = 0; n < 4; ++n) {
;           int col = bcol + wc * 64 + n * 16 + fq * 4;
;           float4 v = make_float4(0.f, 0.f, 0.f, 0.f);
;           if (valid) {
;             v = *(float4*)(hr + col);
;             v.x += acc[m][n][0]; v.y += acc[m][n][1]; v.z += acc[m][n][2]; v.w += acc[m][n][3];
;             *(float4*)(hr + col) = v;
.LBB0_1029:
	v_mov_b32_e32 v18, 0
	v_mov_b32_e32 v19, 0
	v_mov_b32_e32 v16, 0
	v_mov_b32_e32 v17, 0
	s_and_saveexec_b64 s[14:15], s[4:5]
	s_cbranch_execz .LBB0_1031
	v_lshl_add_u64 v[20:21], v[0:1], 2, v[30:31]
	global_load_dwordx4 v[16:19], v[20:21], off offset:64
	s_waitcnt vmcnt(0)
	v_pk_add_f32 v[16:17], v[12:13], v[16:17]
	v_pk_add_f32 v[18:19], v[14:15], v[18:19]
	global_store_dwordx4 v[20:21], v[16:19], off offset:64 sc1

; template <int MODE, bool SWAP, int MT>
; DI void gemm_tile(const int wv_, const Params& p, const u16* __restrict__ A, const u16* __restrict__ Bt, int brow, int bcol, char* smem, const float* gnext) {
;     ...
;         for (int n = 0; n < 4; ++n) {
;           int col = bcol + wc * 64 + n * 16 + fq * 4;
;           float4 v = make_float4(0.f, 0.f, 0.f, 0.f);
;           if (valid) {
;             v = *(float4*)(hr + col);
;             v.x += acc[m][n][0]; v.y += acc[m][n][1]; v.z += acc[m][n][2]; v.w += acc[m][n][3];
;             *(float4*)(hr + col) = v;
.LBB0_1033:
	v_mov_b32_e32 v14, 0
	v_mov_b32_e32 v15, 0
	v_mov_b32_e32 v12, 0
	v_mov_b32_e32 v13, 0
	s_and_saveexec_b64 s[14:15], s[4:5]
	s_cbranch_execz .LBB0_1035
	v_lshl_add_u64 v[16:17], v[0:1], 2, v[30:31]
	global_load_dwordx4 v[12:15], v[16:17], off offset:128
	s_waitcnt vmcnt(0)
	v_pk_add_f32 v[12:13], v[8:9], v[12:13]
	v_pk_add_f32 v[14:15], v[10:11], v[14:15]
	global_store_dwordx4 v[16:17], v[12:15], off offset:128 sc1

; template <int MODE, bool SWAP, int MT>
; DI void gemm_tile(const int wv_, const Params& p, const u16* __restrict__ A, const u16* __restrict__ Bt, int brow, int bcol, char* smem, const float* gnext) {
;     ...
;         for (int n = 0; n < 4; ++n) {
;           int col = bcol + wc * 64 + n * 16 + fq * 4;
;           float4 v = make_float4(0.f, 0.f, 0.f, 0.f);
;           if (valid) {
;             v = *(float4*)(hr + col);
;             v.x += acc[m][n][0]; v.y += acc[m][n][1]; v.z += acc[m][n][2]; v.w += acc[m][n][3];
;             *(float4*)(hr + col) = v;
.LBB0_1039:
	v_lshl_add_u64 v[12:13], v[0:1], 2, v[30:31]
	global_load_dwordx4 v[8:11], v[12:13], off offset:192
	s_waitcnt vmcnt(0)
	v_pk_add_f32 v[8:9], v[4:5], v[8:9]
	v_pk_add_f32 v[10:11], v[6:7], v[10:11]
	global_store_dwordx4 v[12:13], v[8:11], off offset:192 sc1
	s_or_b64 exec, exec, s[14:15]
	s_and_b64 vcc, exec, s[0:1]
	s_cbranch_vccnz .LBB0_1000
